# N2 uniform branch state fully scalar (v141-v143 removed)
# speedup vs baseline: 1.0062x; 1.0062x over previous
; __device__ void phaseN2_task(const Params& p, int task, char* lds, bf16_t* ydst, int ystride, volatile unsigned* uex, char* ldsb) {
;     ...
;             if (nbr == 2) break;
;             br = nbr; j = nj;
.LBB0_617:
	s_or_b64 exec, exec, s[6:7]
	s_cmp_eq_u32 s52, 2
	s_cselect_b64 vcc, -1, 0
	s_or_b64 s[8:9], vcc, s[8:9]
	v_mov_b32_e32 v102, v97
	v_mov_b32_e32 v103, v88
	s_mov_b32 s34, s52
	s_mov_b32 s35, s51
	s_andn2_b64 exec, exec, s[8:9]
	s_cbranch_execz .LBB0_593
	.p2alignl 6, 3212836864

; __device__ void phaseN2_task(const Params& p, int task, char* lds, bf16_t* ydst, int ystride, volatile unsigned* uex, char* ldsb) {
;     ...
;             if (nbr < 2) {
;                 const bf16_t* kb = Z + (rowb + nj * 64) * ZC + (nbr ? ZKW : ZKS) + g * 64;
;                 kreg = *(const u32x4*)(kb + (size_t)kkey * ZC + kch);
;                 vreg = *(const u32x4*)(vtb + (size_t)nbr * (8 * 2 * 64) * SEQ + nj * 64);
;             }
;             int klo = 0, khi = -1;
;             if (br == 0) { if ((mysel >> j) & 1u) khi = t - j * 64; }
;             else { khi = t - j * 64; klo = t - 511 - j * 64; }
;             klo = klo < 0 ? 0 : klo;
;             khi = khi > 63 ? 63 : khi;
;             nsa_block_step(Ks, VT, qf, O, m, l, klo, khi, r, q);
.Ln2_t_next:
	s_lshl_b32 s50, s51, 6
	s_add_i32 s53, s50, s88
	s_mul_i32 s53, s53, s97
	s_movk_i32 s62, 0x2400
	s_cmp_eq_u32 s52, 0
	s_cselect_b32 s62, 0x2200, s62
	s_add_i32 s53, s53, s62
	s_add_i32 s53, s53, s84
	s_add_u32 s58, s90, s53
	s_addc_u32 s59, s91, 0
	s_lshl_b32 s62, s52, 22
	s_lshl_b32 s50, s50, 1
	s_add_i32 s62, s62, s50
	s_add_u32 s60, s56, s62
	s_addc_u32 s61, s57, 0
	s_lshl_b32 s53, s35, 6
	s_sub_i32 s50, 31, s35
	s_barrier
	s_waitcnt vmcnt(1)
	ds_write_b128 v136, v[16:19]
	s_waitcnt vmcnt(0)
	ds_write_b128 v138, v[20:23] offset:18432
	v_subrev_u32_e32 v88, s53, v126
	s_cmp_eq_u32 s34, 0
	s_cbranch_scc1 .Ln2_t_sel
	v_subrev_u32_e32 v97, s53, v134
	v_max_i32_e32 v97, 0, v97
	s_branch .Ln2_t_k

; __device__ __forceinline__ void nsa_block_step(const bf16_t* Ks, const bf16_t* VT, const bf16x8 (&qf)[2][2], f32x4 (&O)[2][4], float (&m)[2], float (&l)[2],
;                                                int klo, int khi, int r, int q) {
;     ...
;     bf16x8 pbv[2][2];
; #pragma unroll
;     for (int x = 0; x < 2; x++) {
;         float mx = fmaxf(fmaxf(fmaxf(s[x][0][0], s[x][0][1]), fmaxf(s[x][0][2], s[x][0][3])), fmaxf(fmaxf(s[x][1][0], s[x][1][1]), fmaxf(s[x][1][2], s[x][1][3])));
;         mx = fmaxf(mx, fmaxf(fmaxf(fmaxf(s[x][2][0], s[x][2][1]), fmaxf(s[x][2][2], s[x][2][3])), fmaxf(fmaxf(s[x][3][0], s[x][3][1]), fmaxf(s[x][3][2], s[x][3][3]))));
;         mx = xrow_max(mx);
;         const float mnew = fmaxf(m[x], mx);
.LBB0_628:
	v_max3_f32 v88, v80, v81, v82
	v_max3_f32 v164, v68, v69, v70
	v_max3_f32 v97, v72, v73, v74
	v_max3_f32 v165, v64, v65, v66
	v_max3_f32 v104, v84, v85, v86
	v_max3_f32 v166, v60, v61, v62
	v_max3_f32 v105, v76, v77, v78
	v_max3_f32 v167, v56, v57, v58
	v_max3_f32 v88, v88, v83, v75
	v_max3_f32 v164, v164, v71, v67
	v_max3_f32 v97, v97, v87, v79
	v_max3_f32 v165, v165, v63, v59
	v_max3_f32 v88, v88, v97, v104
	v_max3_f32 v164, v164, v165, v166
	v_max_f32_e32 v88, v88, v105
	v_max_f32_e32 v164, v164, v167
	v_cmp_gt_f32_e32 vcc, v88, v178
	v_cmp_gt_f32_e64 s[46:47], v164, v179
	s_or_b64 vcc, vcc, s[46:47]
	s_cbranch_vccz .Ln2_fast
; __device__ __forceinline__ float exp2f_(float x) { return __builtin_amdgcn_exp2f(x); }
; __device__ __forceinline__ f32x4 mfma16(bf16x8 a, bf16x8 b, f32x4 c) { return __builtin_amdgcn_mfma_f32_16x16x32_bf16(a, b, c, 0, 0, 0); }
; __device__ __forceinline__ void nsa_block_step(const bf16_t* Ks, const bf16_t* VT, const bf16x8 (&qf)[2][2], f32x4 (&O)[2][4], float (&m)[2], float (&l)[2],
;                                                int klo, int khi, int r, int q) {
;     ...
;     bf16x8 pbv[2][2];
; #pragma unroll
;     for (int x = 0; x < 2; x++) {
;         float mx = fmaxf(fmaxf(fmaxf(s[x][0][0], s[x][0][1]), fmaxf(s[x][0][2], s[x][0][3])), fmaxf(fmaxf(s[x][1][0], s[x][1][1]), fmaxf(s[x][1][2], s[x][1][3])));
;         mx = fmaxf(mx, fmaxf(fmaxf(fmaxf(s[x][2][0], s[x][2][1]), fmaxf(s[x][2][2], s[x][2][3])), fmaxf(fmaxf(s[x][3][0], s[x][3][1]), fmaxf(s[x][3][2], s[x][3][3]))));
;         mx = xrow_max(mx);
;         const float mnew = fmaxf(m[x], mx);
;         const float alpha = exp2f_(m[x] - mnew);
;         m[x] = mnew;
;         float ls = 0.f;
; #pragma unroll
;         for (int kt = 0; kt < 4; kt++)
; #pragma unroll
;             for (int j = 0; j < 4; j++) { const float pv = exp2f_(s[x][kt][j] - mnew); s[x][kt][j] = pv; ls += pv; }
;         l[x] = l[x] * alpha + ls;
; #pragma unroll
;         for (int dt = 0; dt < 4; dt++) O[x][dt] *= alpha;
; #pragma unroll
;         for (int s2 = 0; s2 < 2; s2++) {
;             const u32x4 t4 = {pack2(s[x][2 * s2][0], s[x][2 * s2][1]), pack2(s[x][2 * s2][2], s[x][2 * s2][3]),
;                               pack2(s[x][2 * s2 + 1][0], s[x][2 * s2 + 1][1]), pack2(s[x][2 * s2 + 1][2], s[x][2 * s2 + 1][3])};
;             pbv[x][s2] = __builtin_bit_cast(bf16x8, t4);
;         }
;     }
; #pragma unroll
;     for (int s2 = 0; s2 < 2; s2++)
; #pragma unroll
;         for (int dt = 0; dt < 4; dt++) {
;             const u32x2 lo = *(const u32x2*)(VT + (dt * 16 + r) * 72 + (2 * s2) * 16 + 4 * q);
;             const u32x2 hi = *(const u32x2*)(VT + (dt * 16 + r) * 72 + (2 * s2 + 1) * 16 + 4 * q);
;             const bf16x8 va = mk_frag(lo, hi);
; #pragma unroll
;             for (int x = 0; x < 2; x++) O[x][dt] = mfma16(va, pbv[x][s2], O[x][dt]);
;         }
; __device__ void phaseN2_task(const Params& p, int task, char* lds, bf16_t* ydst, int ystride, volatile unsigned* uex, char* ldsb) {
;     ...
;             if (nbr != br) {
	v_add_f32_e32 v180, v103, v176
	v_add_f32_e32 v182, v102, v177
	v_mov_b32_e32 v97, v88
	v_mov_b32_e32 v165, v164
	s_nop 0
	v_permlane16_swap_b32_e32 v88, v97
	s_nop 0
	v_permlane16_swap_b32_e32 v164, v165
	v_max_f32_e32 v88, v88, v97
	v_max_f32_e32 v164, v164, v165
	v_mov_b32_e32 v97, v88
	v_mov_b32_e32 v165, v164
	s_nop 0
	v_permlane32_swap_b32_e32 v88, v97
	s_nop 0
	v_permlane32_swap_b32_e32 v164, v165
	v_max3_f32 v88, v180, v88, v97
	v_sub_f32_e32 v72, v72, v88
	v_exp_f32_e32 v105, v72
	v_sub_f32_e32 v72, v73, v88
	v_exp_f32_e32 v109, v72
	v_sub_f32_e32 v72, v74, v88
	v_exp_f32_e32 v107, v72
	v_sub_f32_e32 v72, v75, v88
	v_sub_f32_e32 v80, v80, v88
	v_exp_f32_e32 v111, v72
	v_sub_f32_e32 v72, v84, v88
	v_exp_f32_e32 v117, v80
	v_sub_f32_e32 v80, v81, v88
	v_exp_f32_e32 v73, v72
	v_sub_f32_e32 v72, v85, v88
	v_exp_f32_e32 v113, v80
	v_sub_f32_e32 v80, v82, v88
	v_exp_f32_e32 v75, v72
	v_sub_f32_e32 v72, v86, v88
	v_exp_f32_e32 v115, v80
	v_sub_f32_e32 v80, v83, v88
	v_exp_f32_e32 v83, v72
	v_sub_f32_e32 v72, v87, v88
	v_exp_f32_e32 v81, v72
	v_sub_f32_e32 v72, v76, v88
	v_exp_f32_e32 v85, v72
	v_sub_f32_e32 v72, v77, v88
	v_exp_f32_e32 v87, v72
	v_sub_f32_e32 v72, v78, v88
	v_exp_f32_e32 v77, v72
	v_sub_f32_e32 v72, v79, v88
	v_exp_f32_e32 v79, v72
	v_sub_f32_e32 v97, v180, v88
	v_exp_f32_e32 v103, v80
	v_exp_f32_e32 v76, v97
	v_max3_f32 v97, v182, v164, v165
	v_sub_f32_e32 v64, v64, v97
	v_sub_f32_e32 v68, v68, v97
	v_exp_f32_e32 v104, v64
	v_sub_f32_e32 v64, v65, v97
	v_sub_f32_e32 v78, v182, v97
	v_exp_f32_e32 v116, v68
	v_sub_f32_e32 v68, v69, v97
	v_exp_f32_e32 v108, v64
	v_sub_f32_e32 v64, v66, v97
	v_exp_f32_e32 v112, v68
	v_exp_f32_e32 v106, v64
	v_sub_f32_e32 v64, v67, v97
	v_sub_f32_e32 v60, v60, v97
	v_exp_f32_e32 v160, v78
	v_add_u32_e32 v78, 0x4800, v135
	v_exp_f32_e32 v110, v64
	v_exp_f32_e32 v72, v60
	v_sub_f32_e32 v60, v61, v97
	ds_read2_b64 v[64:67], v78 offset1:4
	v_exp_f32_e32 v74, v60
	v_sub_f32_e32 v60, v62, v97
	v_sub_f32_e32 v68, v70, v97
	v_exp_f32_e32 v82, v60
	v_sub_f32_e32 v60, v63, v97
	v_exp_f32_e32 v114, v68
	v_sub_f32_e32 v68, v71, v97
	v_pk_add_f32 v[156:157], v[116:117], 0 op_sel_hi:[1,0]
	v_exp_f32_e32 v80, v60
	v_cvt_pk_bf16_f32 v60, v116, v112
	v_add_u32_e32 v116, 0x5000, v135
	v_exp_f32_e32 v102, v68
	ds_read2_b64 v[68:71], v116 offset0:32 offset1:36
	v_mov_b32_e32 v161, v76
	v_pk_mul_f32 v[146:147], v[54:55], v[76:77] op_sel_hi:[1,0]
	v_pk_mul_f32 v[144:145], v[52:53], v[76:77] op_sel_hi:[1,0]
	v_cvt_pk_bf16_f32 v52, v117, v113
	v_cvt_pk_bf16_f32 v53, v115, v103
	v_cvt_pk_bf16_f32 v54, v105, v109
	v_cvt_pk_bf16_f32 v55, v107, v111
	v_pk_mul_f32 v[38:39], v[38:39], v[160:161] op_sel_hi:[1,0]
	v_pk_mul_f32 v[36:37], v[36:37], v[160:161] op_sel_hi:[1,0]
	v_cvt_pk_bf16_f32 v61, v114, v102
	v_cvt_pk_bf16_f32 v62, v104, v108
	v_cvt_pk_bf16_f32 v63, v106, v110
	v_add_u32_e32 v117, 0x5800, v135
	s_waitcnt lgkmcnt(1)
	v_mfma_f32_16x16x32_bf16 v[144:147], v[64:67], v[52:55], v[144:147]
	v_mul_f32_e64 v150, v50, v76
	v_mul_f32_e64 v151, v51, v76
	v_pk_mul_f32 v[148:149], v[48:49], v[76:77] op_sel_hi:[1,0]
	v_pk_mul_f32 v[34:35], v[34:35], v[160:161] op_sel_hi:[1,0]
	v_mfma_f32_16x16x32_bf16 v[36:39], v[64:67], v[60:63], v[36:39]
	ds_read2_b64 v[64:67], v117 offset0:64 offset1:68
	v_pk_mul_f32 v[32:33], v[32:33], v[160:161] op_sel_hi:[1,0]
	v_add_u32_e32 v162, 0x6000, v135
	s_waitcnt lgkmcnt(1)
	v_mfma_f32_16x16x32_bf16 v[148:151], v[68:71], v[52:55], v[148:151]
	v_mul_f32_e64 v50, v46, v76
	v_mul_f32_e64 v51, v47, v76
	v_pk_mul_f32 v[48:49], v[44:45], v[76:77] op_sel_hi:[1,0]
	v_pk_mul_f32 v[46:47], v[42:43], v[76:77] op_sel_hi:[1,0]
	v_mfma_f32_16x16x32_bf16 v[32:35], v[68:71], v[60:63], v[32:35]
	ds_read2_b64 v[68:71], v162 offset0:96 offset1:100
	v_pk_mul_f32 v[44:45], v[40:41], v[76:77] op_sel_hi:[1,0]
	v_sub_f32_e32 v56, v56, v97
	s_waitcnt lgkmcnt(1)
	v_mfma_f32_16x16x32_bf16 v[152:155], v[64:67], v[52:55], v[48:51]
	v_mul_f32_e64 v30, v30, v160
	v_mul_f32_e64 v31, v31, v160
	v_pk_mul_f32 v[28:29], v[28:29], v[160:161] op_sel_hi:[1,0]
	v_exp_f32_e32 v84, v56
	v_sub_f32_e32 v48, v58, v97
	v_exp_f32_e32 v76, v48
	ds_read2_b64 v[48:51], v78 offset0:8 offset1:12
	v_sub_f32_e32 v56, v57, v97
	v_mfma_f32_16x16x32_bf16 v[28:31], v[64:67], v[60:63], v[28:31]
	v_exp_f32_e32 v86, v56
	v_cvt_pk_bf16_f32 v40, v73, v75
	v_cvt_pk_bf16_f32 v41, v83, v81
	s_waitcnt lgkmcnt(1)
	v_mfma_f32_16x16x32_bf16 v[64:67], v[68:71], v[52:55], v[44:47]
	v_cvt_pk_bf16_f32 v42, v85, v87
	v_cvt_pk_bf16_f32 v43, v77, v79
	v_cvt_pk_bf16_f32 v56, v72, v74
	v_sub_f32_e32 v44, v59, v97
	v_exp_f32_e32 v78, v44
	ds_read2_b64 v[44:47], v116 offset0:40 offset1:44
	v_cvt_pk_bf16_f32 v57, v82, v80
	v_cvt_pk_bf16_f32 v58, v84, v86
	v_cvt_pk_bf16_f32 v59, v76, v78
	v_pk_mul_f32 v[26:27], v[26:27], v[160:161] op_sel_hi:[1,0]
	v_pk_mul_f32 v[24:25], v[24:25], v[160:161] op_sel_hi:[1,0]
	s_waitcnt lgkmcnt(1)
	v_mfma_f32_16x16x32_bf16 v[52:55], v[48:51], v[40:43], v[144:147]
	s_cmp_lg_u32 s52, s34
	s_cselect_b64 vcc, -1, 0
	v_mfma_f32_16x16x32_bf16 v[36:39], v[48:51], v[56:59], v[36:39]
	v_add_f32_e64 v48, v112, v156
	v_add_f32_e64 v49, v113, v157
	v_mfma_f32_16x16x32_bf16 v[24:27], v[68:71], v[60:63], v[24:27]
	v_add_f32_e64 v68, v114, v48
	v_add_f32_e64 v69, v115, v49
	ds_read2_b64 v[60:63], v117 offset0:72 offset1:76
	v_pk_add_f32 v[68:69], v[102:103], v[68:69]
	s_waitcnt lgkmcnt(1)
	v_mfma_f32_16x16x32_bf16 v[48:51], v[44:47], v[40:43], v[148:151]
	v_add_f32_e64 v68, v104, v68
	v_add_f32_e64 v69, v105, v69
	v_pk_add_f32 v[68:69], v[108:109], v[68:69]
	v_mfma_f32_16x16x32_bf16 v[32:35], v[44:47], v[56:59], v[32:35]
	v_add_f32_e64 v44, v106, v68
	v_add_f32_e64 v45, v107, v69
	ds_read2_b64 v[68:71], v162 offset0:104 offset1:108
	v_pk_add_f32 v[102:103], v[110:111], v[44:45]
	s_waitcnt lgkmcnt(1)
	v_mfma_f32_16x16x32_bf16 v[44:47], v[60:63], v[40:43], v[152:155]
	v_add_f32_e64 v72, v72, v102
	v_add_f32_e64 v73, v73, v103
	v_pk_add_f32 v[72:73], v[74:75], v[72:73]
	v_mfma_f32_16x16x32_bf16 v[28:31], v[60:63], v[56:59], v[28:31]
	v_add_f32_e64 v72, v82, v72
	v_add_f32_e64 v73, v83, v73
	v_pk_add_f32 v[60:61], v[80:81], v[72:73]
	s_waitcnt lgkmcnt(0)
	v_mfma_f32_16x16x32_bf16 v[40:43], v[68:71], v[40:43], v[64:67]
	v_add_f32_e64 v60, v84, v60
	v_add_f32_e64 v61, v85, v61
	v_pk_add_f32 v[60:61], v[86:87], v[60:61]
	v_mfma_f32_16x16x32_bf16 v[24:27], v[68:71], v[56:59], v[24:27]
	v_add_f32_e64 v60, v76, v60
	v_add_f32_e64 v61, v77, v61
	v_pk_add_f32 v[60:61], v[78:79], v[60:61]
	s_nop 0
	v_pk_fma_f32 v[100:101], v[100:101], v[160:161], v[60:61]
	s_mov_b32 s45, 0xf0a18f08
	v_sub_f32_e32 v88, v88, v176
	v_sub_f32_e32 v97, v97, v177
	v_cmp_lt_f32_e64 s[46:47], v88, s45
	v_cmp_lt_f32_e64 s[48:49], v97, s45
	v_sub_f32_e32 v176, 0, v88
	v_sub_f32_e32 v177, 0, v97
	v_cndmask_b32_e64 v176, v176, 0, s[46:47]
	v_cndmask_b32_e64 v177, v177, 0, s[48:49]
	v_cndmask_b32_e64 v178, 4.0, v123, s[46:47]
	v_cndmask_b32_e64 v179, 4.0, v123, s[48:49]

; __device__ __forceinline__ float exp2f_(float x) { return __builtin_amdgcn_exp2f(x); }
; __device__ __forceinline__ f32x4 mfma16(bf16x8 a, bf16x8 b, f32x4 c) { return __builtin_amdgcn_mfma_f32_16x16x32_bf16(a, b, c, 0, 0, 0); }
; __device__ __forceinline__ void nsa_block_step(const bf16_t* Ks, const bf16_t* VT, const bf16x8 (&qf)[2][2], f32x4 (&O)[2][4], float (&m)[2], float (&l)[2],
;                                                int klo, int khi, int r, int q) {
;     ...
;         float ls = 0.f;
; #pragma unroll
;         for (int kt = 0; kt < 4; kt++)
; #pragma unroll
;             for (int j = 0; j < 4; j++) { const float pv = exp2f_(s[x][kt][j] - mnew); s[x][kt][j] = pv; ls += pv; }
;         l[x] = l[x] * alpha + ls;
; #pragma unroll
;         for (int dt = 0; dt < 4; dt++) O[x][dt] *= alpha;
; #pragma unroll
;         for (int s2 = 0; s2 < 2; s2++) {
;             const u32x4 t4 = {pack2(s[x][2 * s2][0], s[x][2 * s2][1]), pack2(s[x][2 * s2][2], s[x][2 * s2][3]),
;                               pack2(s[x][2 * s2 + 1][0], s[x][2 * s2 + 1][1]), pack2(s[x][2 * s2 + 1][2], s[x][2 * s2 + 1][3])};
;             pbv[x][s2] = __builtin_bit_cast(bf16x8, t4);
;         }
;     }
; #pragma unroll
;     for (int s2 = 0; s2 < 2; s2++)
; #pragma unroll
;         for (int dt = 0; dt < 4; dt++) {
;             const u32x2 lo = *(const u32x2*)(VT + (dt * 16 + r) * 72 + (2 * s2) * 16 + 4 * q);
;             const u32x2 hi = *(const u32x2*)(VT + (dt * 16 + r) * 72 + (2 * s2 + 1) * 16 + 4 * q);
;             const bf16x8 va = mk_frag(lo, hi);
; #pragma unroll
;             for (int x = 0; x < 2; x++) O[x][dt] = mfma16(va, pbv[x][s2], O[x][dt]);
;         }
; __device__ void phaseN2_task(const Params& p, int task, char* lds, bf16_t* ydst, int ystride, volatile unsigned* uex, char* ldsb) {
;     ...
;             if (nbr != br) {
.Ln2_fast:
	ds_read2_b64 v[200:203], v216 offset1:4
	ds_read2_b64 v[204:207], v217 offset0:32 offset1:36
	ds_read2_b64 v[208:211], v218 offset0:64 offset1:68
	ds_read2_b64 v[212:215], v219 offset0:96 offset1:100
	v_exp_f32_e32 v80, v80
	v_exp_f32_e32 v81, v81
	v_exp_f32_e32 v82, v82
	v_exp_f32_e32 v83, v83
	v_exp_f32_e32 v72, v72
	v_exp_f32_e32 v73, v73
	v_exp_f32_e32 v74, v74
	v_exp_f32_e32 v75, v75
	ds_read2_b64 v[224:227], v216 offset0:8 offset1:12
	ds_read2_b64 v[228:231], v217 offset0:40 offset1:44
	v_exp_f32_e32 v68, v68
	v_exp_f32_e32 v69, v69
	v_exp_f32_e32 v70, v70
	v_exp_f32_e32 v71, v71
	v_exp_f32_e32 v64, v64
	v_exp_f32_e32 v65, v65
	v_exp_f32_e32 v66, v66
	v_exp_f32_e32 v67, v67
	ds_read2_b64 v[232:235], v218 offset0:72 offset1:76
	ds_read2_b64 v[236:239], v219 offset0:104 offset1:108
	v_cvt_pk_bf16_f32 v184, v80, v81
	v_cvt_pk_bf16_f32 v185, v82, v83
	v_cvt_pk_bf16_f32 v186, v72, v73
	v_cvt_pk_bf16_f32 v187, v74, v75
	v_cvt_pk_bf16_f32 v192, v68, v69
	v_cvt_pk_bf16_f32 v193, v70, v71
	v_cvt_pk_bf16_f32 v194, v64, v65
	v_cvt_pk_bf16_f32 v195, v66, v67
	v_exp_f32_e32 v84, v84
	v_exp_f32_e32 v85, v85
	s_waitcnt lgkmcnt(7)
	v_mfma_f32_16x16x32_bf16 v[52:55], v[200:203], v[184:187], v[52:55]
	v_exp_f32_e32 v86, v86
	v_exp_f32_e32 v87, v87
	v_mfma_f32_16x16x32_bf16 v[36:39], v[200:203], v[192:195], v[36:39]
	v_exp_f32_e32 v76, v76
	v_exp_f32_e32 v77, v77
	s_waitcnt lgkmcnt(6)
	v_mfma_f32_16x16x32_bf16 v[48:51], v[204:207], v[184:187], v[48:51]
	v_exp_f32_e32 v78, v78
	v_exp_f32_e32 v79, v79
	v_mfma_f32_16x16x32_bf16 v[32:35], v[204:207], v[192:195], v[32:35]
	v_exp_f32_e32 v60, v60
	v_exp_f32_e32 v61, v61
	s_waitcnt lgkmcnt(5)
	v_mfma_f32_16x16x32_bf16 v[44:47], v[208:211], v[184:187], v[44:47]
	v_exp_f32_e32 v62, v62
	v_exp_f32_e32 v63, v63
	v_mfma_f32_16x16x32_bf16 v[28:31], v[208:211], v[192:195], v[28:31]
	v_exp_f32_e32 v56, v56
	v_exp_f32_e32 v57, v57
	s_waitcnt lgkmcnt(4)
	v_mfma_f32_16x16x32_bf16 v[40:43], v[212:215], v[184:187], v[40:43]
	v_exp_f32_e32 v58, v58
	v_exp_f32_e32 v59, v59
	v_mfma_f32_16x16x32_bf16 v[24:27], v[212:215], v[192:195], v[24:27]
	v_cvt_pk_bf16_f32 v188, v84, v85
	v_cvt_pk_bf16_f32 v189, v86, v87
	v_cvt_pk_bf16_f32 v190, v76, v77
	v_cvt_pk_bf16_f32 v191, v78, v79
	v_cvt_pk_bf16_f32 v196, v60, v61
	v_cvt_pk_bf16_f32 v197, v62, v63
	v_cvt_pk_bf16_f32 v198, v56, v57
	v_cvt_pk_bf16_f32 v199, v58, v59
	v_add_f32_e32 v221, v80, v81
	v_add_f32_e32 v220, v68, v69
	s_waitcnt lgkmcnt(3)
	v_mfma_f32_16x16x32_bf16 v[52:55], v[224:227], v[188:191], v[52:55]
	v_add_f32_e32 v221, v221, v82
	v_add_f32_e32 v220, v220, v70
	v_mfma_f32_16x16x32_bf16 v[36:39], v[224:227], v[196:199], v[36:39]
	v_add_f32_e32 v221, v221, v83
	v_add_f32_e32 v220, v220, v71
	s_waitcnt lgkmcnt(2)
	v_mfma_f32_16x16x32_bf16 v[48:51], v[228:231], v[188:191], v[48:51]
	v_add_f32_e32 v221, v221, v72
	v_add_f32_e32 v220, v220, v64
	v_mfma_f32_16x16x32_bf16 v[32:35], v[228:231], v[196:199], v[32:35]
	v_add_f32_e32 v221, v221, v73
	v_add_f32_e32 v220, v220, v65
	s_waitcnt lgkmcnt(1)
	v_mfma_f32_16x16x32_bf16 v[44:47], v[232:235], v[188:191], v[44:47]
	v_add_f32_e32 v221, v221, v74
	v_add_f32_e32 v220, v220, v66
	v_mfma_f32_16x16x32_bf16 v[28:31], v[232:235], v[196:199], v[28:31]
	v_add_f32_e32 v221, v221, v75
	v_add_f32_e32 v220, v220, v67
	s_waitcnt lgkmcnt(0)
	v_mfma_f32_16x16x32_bf16 v[40:43], v[236:239], v[188:191], v[40:43]
	v_add_f32_e32 v221, v221, v84
	v_add_f32_e32 v220, v220, v60
	v_mfma_f32_16x16x32_bf16 v[24:27], v[236:239], v[196:199], v[24:27]
	v_add_f32_e32 v221, v221, v85
	v_add_f32_e32 v220, v220, v61
	v_add_f32_e32 v221, v221, v86
	v_add_f32_e32 v220, v220, v62
	v_add_f32_e32 v221, v221, v87
	v_add_f32_e32 v220, v220, v63
	v_add_f32_e32 v221, v221, v76
	v_add_f32_e32 v220, v220, v56
	v_add_f32_e32 v221, v221, v77
	v_add_f32_e32 v220, v220, v57
	v_add_f32_e32 v221, v221, v78
	v_add_f32_e32 v220, v220, v58
	v_add_f32_e32 v221, v221, v79
	v_add_f32_e32 v220, v220, v59
	s_cmp_lg_u32 s52, s34
	s_cselect_b64 vcc, -1, 0
	v_mov_b32_e32 v88, v103
	v_mov_b32_e32 v97, v102
	v_pk_add_f32 v[100:101], v[100:101], v[220:221]
	s_branch .Ln2_tail
